# code placement: MLA tile loop shifted by 4 bytes (one s_nop in the preheader) so the loop head sits at 0 mod 8
# speedup vs baseline: 1.0041x; 1.0041x over previous
; #define LAS __attribute__((address_space(3)))
; #define SB() __builtin_amdgcn_sched_barrier(0)
; template <int VAR>
; __device__ __forceinline__ void attn_phase(LAS unsigned char* lds, const AttnP P, int vcu, int G, int wave_s) {
;     ...
;             if (need_c && __any(rmc > THR)) {
;                 const float dl = __builtin_fmaxf(rmc, 0.f), f = __builtin_amdgcn_exp2f(-dl);
;                 mref += dl; lrun *= f;
; #pragma unroll
;                 for (int r = 0; r < 16; ++r) { if (USE_NEGM) { pc0[r] -= dl; pc1[r] -= dl; negm[r] = -mref; } o0[r] *= f; o1[r] *= f; }
;             }
;             f32x16 pn0 = {}, pn1 = {};
;             float rmn = -1e30f;
;             if (VAR != 2 && need_c && need_n) {
;                 const LAS unsigned char* kt_ = lds + ((t + 1) & 1) * ABUF; const LAS unsigned char* vt_ = lds + (t & 1) * ABUF + KT_BYTES;
;                 bf16x8 kf[2 * ND0], vf[8]; u32x4 w0, w1, w2, w3; float sacc = 0.f;
;     ...
;                 if (ND0 == 6) {
;                     KR1(0); KR1(1); KR1(2); KR1(3); SB();
.Lmla_noprio:
	ds_read_b128 v[182:185], v174 offset:22528
	ds_read_b128 v[186:189], v174 offset:29184
	ds_read_b128 v[190:193], v174 offset:22560
	ds_read_b128 v[194:197], v174 offset:29216
	s_nop 0
	v_cmp_lt_f32_e32 vcc, s66, v167
